# panel hand-off polls of P8 / P9 / P12: four polls in flight (ring) with fallback to the original retry loop
# baseline (speedup 1.0000x reference)
; __device__ __forceinline__ unsigned xb_ld(unsigned* p)              { return __hip_atomic_load(p, __ATOMIC_RELAXED, __HIP_MEMORY_SCOPE_AGENT); }
; #define XB_SPIN(cond, bar) do { unsigned _sp = 0; while (cond) { __builtin_amdgcn_s_sleep(1); \
;     if ((++_sp & 255u) == 0u) { if (xb_ld(&(bar)[XB_TMO])) break; if (_sp > XB_SPIN_CAP) { atomicAdd(&(bar)[XB_TMO], 1u); break; } } } } while (0)
; __global__ void __launch_bounds__(NTHR, 2) k_main(Args a) {
;     ...
;         for (int i = 0; S.next(i, u); ++i) {
;             __syncthreads();
;             if (tid == 0) { unsigned* cw = &((unsigned*)ws)[12288 + 16 * u.pm]; XB_SPIN(xb_ld(cw) < (unsigned)(D / 256), (unsigned*)ws);
;                 __builtin_amdgcn_fence(__ATOMIC_ACQUIRE, "agent"); asm volatile("s_waitcnt vmcnt(0)" ::: "memory"); }
.LBB0_549:
	s_barrier
	s_and_saveexec_b64 s[10:11], s[0:1]
	s_cbranch_execz .LBB0_564
	buffer_inv sc1
	s_lshl_b32 s24, s43, 4
	s_ashr_i32 s25, s24, 31
	s_lshl_b64 s[24:25], s[24:25], 2
	s_add_u32 s24, s90, s24
	s_addc_u32 s25, s91, s25
	global_load_dword v2, v28, s[24:25] sc1
	s_add_u32 s24, s24, 0xc000
	s_addc_u32 s25, s25, 0
	s_waitcnt vmcnt(0)
	v_cmp_lt_u32_e32 vcc, 3, v2
	s_cbranch_vccnz .LBB0_563
	s_movk_i32 s44, 0x1000
	global_load_dword v236, v19, s[24:25] sc1
	s_sleep 3
	global_load_dword v237, v19, s[24:25] sc1
	s_sleep 3
	global_load_dword v238, v19, s[24:25] sc1
	s_sleep 3
.Lp8_ring:
	global_load_dword v239, v19, s[24:25] sc1
	s_waitcnt vmcnt(3)
	v_cmp_lt_u32_e32 vcc, 3, v236
	s_cbranch_vccnz .Lp8_ring_ok
	global_load_dword v236, v19, s[24:25] sc1
	s_waitcnt vmcnt(3)
	v_cmp_lt_u32_e32 vcc, 3, v237
	s_cbranch_vccnz .Lp8_ring_ok
	global_load_dword v237, v19, s[24:25] sc1
	s_waitcnt vmcnt(3)
	v_cmp_lt_u32_e32 vcc, 3, v238
	s_cbranch_vccnz .Lp8_ring_ok
	global_load_dword v238, v19, s[24:25] sc1
	s_waitcnt vmcnt(3)
	v_cmp_lt_u32_e32 vcc, 3, v239
	s_cbranch_vccnz .Lp8_ring_ok
	s_sub_i32 s44, s44, 1
	s_cmp_lg_u32 s44, 0
	s_cbranch_scc1 .Lp8_ring
	s_waitcnt vmcnt(0)
	s_mov_b32 s44, 1
	s_branch .LBB0_553

; __device__ __forceinline__ unsigned xb_ld(unsigned* p)              { return __hip_atomic_load(p, __ATOMIC_RELAXED, __HIP_MEMORY_SCOPE_AGENT); }
; #define XB_SPIN(cond, bar) do { unsigned _sp = 0; while (cond) { __builtin_amdgcn_s_sleep(1); \
;     if ((++_sp & 255u) == 0u) { if (xb_ld(&(bar)[XB_TMO])) break; if (_sp > XB_SPIN_CAP) { atomicAdd(&(bar)[XB_TMO], 1u); break; } } } } while (0)
; __global__ void __launch_bounds__(NTHR, 2) k_main(Args a) {
;     ...
;         { __syncthreads();
;           if (tid == 0) { pg8::Unit u; for (int i = 0; S.next(i, u); ++i) { unsigned* cw = &((unsigned*)ws)[6144 + 16 * u.pm]; XB_SPIN(xb_ld(cw) < 4u, (unsigned*)ws); }
;               XB_SPIN(xb_ld(&((unsigned*)ws)[14336]) < 256u, (unsigned*)ws);
;               __builtin_amdgcn_fence(__ATOMIC_ACQUIRE, "agent"); asm volatile("s_waitcnt vmcnt(0)" ::: "memory"); }
.LBB0_585:
	s_lshl_b32 s6, s16, 4
	s_ashr_i32 s7, s6, 31
	s_lshl_b64 s[6:7], s[6:7], 2
	s_add_u32 s6, s90, s6
	s_addc_u32 s7, s91, s7
	global_load_dword v7, v1, s[6:7] sc1
	s_add_u32 s6, s6, 0x6000
	s_addc_u32 s7, s7, 0
	s_waitcnt vmcnt(0)
	v_cmp_lt_u32_e32 vcc, 3, v7
	s_cbranch_vccnz .LBB0_576
	s_movk_i32 s17, 0x1000
	global_load_dword v236, v6, s[6:7] sc1
	s_sleep 3
	global_load_dword v237, v6, s[6:7] sc1
	s_sleep 3
	global_load_dword v238, v6, s[6:7] sc1
	s_sleep 3
.Lp9_ring:
	global_load_dword v239, v6, s[6:7] sc1
	s_waitcnt vmcnt(3)
	v_cmp_lt_u32_e32 vcc, 3, v236
	s_cbranch_vccnz .Lp9_ring_ok
	global_load_dword v236, v6, s[6:7] sc1
	s_waitcnt vmcnt(3)
	v_cmp_lt_u32_e32 vcc, 3, v237
	s_cbranch_vccnz .Lp9_ring_ok
	global_load_dword v237, v6, s[6:7] sc1
	s_waitcnt vmcnt(3)
	v_cmp_lt_u32_e32 vcc, 3, v238
	s_cbranch_vccnz .Lp9_ring_ok
	global_load_dword v238, v6, s[6:7] sc1
	s_waitcnt vmcnt(3)
	v_cmp_lt_u32_e32 vcc, 3, v239
	s_cbranch_vccnz .Lp9_ring_ok
	s_sub_i32 s17, s17, 1
	s_cmp_lg_u32 s17, 0
	s_cbranch_scc1 .Lp9_ring
	s_waitcnt vmcnt(0)
	s_mov_b32 s17, 1
	s_branch .LBB0_588

; __device__ __forceinline__ unsigned xb_ld(unsigned* p)              { return __hip_atomic_load(p, __ATOMIC_RELAXED, __HIP_MEMORY_SCOPE_AGENT); }
; #define XB_SPIN(cond, bar) do { unsigned _sp = 0; while (cond) { __builtin_amdgcn_s_sleep(1); \
;     if ((++_sp & 255u) == 0u) { if (xb_ld(&(bar)[XB_TMO])) break; if (_sp > XB_SPIN_CAP) { atomicAdd(&(bar)[XB_TMO], 1u); break; } } } } while (0)
; __global__ void __launch_bounds__(NTHR, 2) k_main(Args a) {
;     ...
;         for (int j = bid; j < NCHUNK; j += nb) {
;             __syncthreads();
;             if (tid == 0) {
;                 unsigned* cw = &((unsigned*)ws)[4096 + 16 * (j >> 2)];
;                 XB_SPIN(xb_ld(cw) < (unsigned)(D / 256), (unsigned*)ws);
;                 __builtin_amdgcn_fence(__ATOMIC_ACQUIRE, "agent");
;                 asm volatile("s_waitcnt vmcnt(0)" ::: "memory");
;             }
.LBB0_648:
	s_barrier
	s_and_saveexec_b64 s[10:11], s[0:1]
	s_cbranch_execz .LBB0_663
	buffer_inv sc1
	s_lshl_b32 s12, s2, 2
	s_and_b32 s12, s12, -16
	s_ashr_i32 s13, s12, 31
	s_lshl_b64 s[12:13], s[12:13], 2
	s_add_u32 s12, s90, s12
	s_addc_u32 s13, s91, s13
	global_load_dword v18, v93, s[12:13] sc1
	s_add_u32 s12, s12, 0x4000
	s_addc_u32 s13, s13, 0
	s_waitcnt vmcnt(0)
	v_cmp_lt_u32_e32 vcc, 3, v18
	s_cbranch_vccnz .LBB0_662
	s_movk_i32 s41, 0x1000
	global_load_dword v236, v83, s[12:13] sc1
	s_sleep 3
	global_load_dword v237, v83, s[12:13] sc1
	s_sleep 3
	global_load_dword v238, v83, s[12:13] sc1
	s_sleep 3
.Lp12_ring:
	global_load_dword v239, v83, s[12:13] sc1
	s_waitcnt vmcnt(3)
	v_cmp_lt_u32_e32 vcc, 3, v236
	s_cbranch_vccnz .Lp12_ring_ok
	global_load_dword v236, v83, s[12:13] sc1
	s_waitcnt vmcnt(3)
	v_cmp_lt_u32_e32 vcc, 3, v237
	s_cbranch_vccnz .Lp12_ring_ok
	global_load_dword v237, v83, s[12:13] sc1
	s_waitcnt vmcnt(3)
	v_cmp_lt_u32_e32 vcc, 3, v238
	s_cbranch_vccnz .Lp12_ring_ok
	global_load_dword v238, v83, s[12:13] sc1
	s_waitcnt vmcnt(3)
	v_cmp_lt_u32_e32 vcc, 3, v239
	s_cbranch_vccnz .Lp12_ring_ok
	s_sub_i32 s41, s41, 1
	s_cmp_lg_u32 s41, 0
	s_cbranch_scc1 .Lp12_ring
	s_waitcnt vmcnt(0)
	s_mov_b32 s41, 1
	s_branch .LBB0_652
